# GEMM K-loop: per-phase s_setprio flips deleted, one static s_setprio 1 for waves 4-7 per unit (strategy 4)
# speedup vs baseline: 1.0022x; 1.0022x over previous
; #define PG8_STAGE(bufoff, gbase, voff) do { _Pragma("unroll") for (int _i = 0; _i < 2; ++_i) \
;         __builtin_amdgcn_global_load_lds((const unsigned*)((const char*)(gbase) + (voff)[_i]), (LAS unsigned*)(lds + (bufoff) + ldsw + _i * 8192), 16, 0, 0); } while (0)
; #define PG8_LDA(dst, b, h) do { _Pragma("unroll") for (int m = 0; m < 4; ++m) _Pragma("unroll") for (int k = 0; k < 2; ++k) dst[m][k] = *(const LAS bf16x8*)(lds + PG8_SA(b, h) + aoff + m * 2048 + k * 1024); } while (0)
; #define PG8_LDB(dst, b, h) do { _Pragma("unroll") for (int n = 0; n < 2; ++n) _Pragma("unroll") for (int k = 0; k < 2; ++k) dst[n][k] = *(const LAS bf16x8*)(lds + PG8_SB(b, h) + boff + n * 2048 + k * 1024); } while (0)
; #define PG8_MMA(ai, bj, At, Bt) do { __builtin_amdgcn_s_setprio(1); _Pragma("unroll") for (int m = 0; m < 4; ++m) _Pragma("unroll") for (int n = 0; n < 2; ++n) _Pragma("unroll") for (int k = 0; k < 2; ++k) \
;         acc[ai][bj][m][n] = __builtin_amdgcn_mfma_f32_16x16x32_bf16(Bt[n][k], At[m][k], acc[ai][bj][m][n], 0, 0, 0); __builtin_amdgcn_s_setprio(0); } while (0)
; #define PG8_WAIT_V(n) asm volatile("s_waitcnt vmcnt(" #n ")" ::: "memory")
; #define PG8_WAIT_L(n) asm volatile("s_waitcnt lgkmcnt(" #n ")" ::: "memory")
; __device__ __forceinline__ void gemm_phase(const int bid, const int nblk, LAS unsigned char* lds, const int garg, const int chunk, const Params& p) {
;     ...
;         for (int t = 0; t < nt; t += 2) {
;             const bool last = (t == nt - 2);
;             const char* a1 = cA + (size_t)(t + 1) * kstep;
;             const char* a2 = last ? nA : cA + (size_t)(t + 2) * kstep; const char* b2 = last ? nB : cB + (size_t)(t + 2) * kstep;
;             const char* a3 = a2 + kstep; const char* b3 = b2 + kstep;
;             PG8_LDB(B0, 0, 0); PG8_SCHED; PG8_LDA(At, 0, 0); PG8_STAGE(PG8_SA(1, 1), a1 + hstepA, voffA);
;             PG8_WAIT_L(8); PG8_BAR; PG8_WAIT_L(0); PG8_MMA(0, 0, At, B0); PG8_BAR; PG8_SCHED;
;             PG8_LDB(B1, 0, 1); PG8_STAGE(PG8_SB(0, 0), b2, voffB);
;             PG8_BAR; PG8_WAIT_L(0); PG8_MMA(0, 1, At, B1); PG8_BAR;
;             PG8_LDA(At, 0, 1); PG8_STAGE(PG8_SA(0, 0), a2, voffA);
;             PG8_BAR; PG8_WAIT_L(0); PG8_MMA(1, 0, At, B0); PG8_BAR; PG8_SCHED;
;             PG8_STAGE(PG8_SB(0, 1), b2 + hstepB, voffB);
;             PG8_WAIT_V(6); PG8_BAR; PG8_MMA(1, 1, At, B1); PG8_BAR;
.LBB0_439:
	v_readlane_b32 s10, v254, 62
	v_readlane_b32 s11, v254, 63
	s_andn2_b64 vcc, exec, s[10:11]
	s_cbranch_vccnz .LBB0_442
	s_add_u32 s2, s2, 0x80
	s_addc_u32 s3, s3, 0
	s_add_u32 s14, s8, 0x100
	s_addc_u32 s15, s9, 0
	s_mov_b32 s8, 0
	v_readfirstlane_b32 s98, v169
	s_nop 3
	s_cmp_ge_u32 s98, 0x100
	s_cbranch_scc0 .Lprio_skip
	s_setprio 1
.Lprio_skip:
	s_waitcnt vmcnt(0)
	s_add_i32 s30, s8, 2
	s_add_u32 s12, s2, 0x80
	s_addc_u32 s9, s3, 0
	s_add_i32 s31, 0, 0x10000
	v_add_u32_e32 v10, s31, v234
	ds_read_b128 v[134:137], v10
	ds_read_b128 v[138:141], v10 offset:1024
	ds_read_b128 v[142:145], v10 offset:2048
	ds_read_b128 v[146:149], v10 offset:3072
	s_cmp_eq_u32 s27, s8
	s_cselect_b32 s8, s74, s12
	s_cselect_b32 s9, s75, s9
	s_cselect_b32 s13, s79, s15
	s_cselect_b32 s12, s78, s14
	v_lshl_add_u64 v[12:13], s[2:3], 0, v[176:177]
	s_add_i32 m0, s65, 0xc000
	ds_read_b128 v[150:153], v240
	ds_read_b128 v[154:157], v240 offset:1024
	ds_read_b128 v[182:185], v240 offset:2048
	ds_read_b128 v[186:189], v240 offset:3072
	ds_read_b128 v[190:193], v240 offset:4096
	ds_read_b128 v[194:197], v240 offset:5120
	ds_read_b128 v[198:201], v240 offset:6144
	ds_read_b128 v[202:205], v240 offset:7168
	global_load_lds_dwordx4 v[12:13], off
	v_lshl_add_u64 v[12:13], s[2:3], 0, v[178:179]
	s_add_i32 m0, s65, 0xe000
	s_nop 0
	global_load_lds_dwordx4 v[12:13], off
	s_waitcnt lgkmcnt(8)
	s_barrier
	s_waitcnt lgkmcnt(0)
	v_mfma_f32_16x16x32_bf16 v[130:133], v[134:137], v[150:153], 0
	v_mfma_f32_16x16x32_bf16 v[126:129], v[142:145], v[150:153], 0
	v_mfma_f32_16x16x32_bf16 v[114:117], v[134:137], v[182:185], 0
	v_mfma_f32_16x16x32_bf16 v[110:113], v[142:145], v[182:185], 0
	v_mfma_f32_16x16x32_bf16 v[98:101], v[134:137], v[190:193], 0
	v_mfma_f32_16x16x32_bf16 v[94:97], v[142:145], v[190:193], 0
	v_mfma_f32_16x16x32_bf16 v[82:85], v[134:137], v[198:201], 0
	v_mfma_f32_16x16x32_bf16 v[78:81], v[142:145], v[198:201], 0
	v_mfma_f32_16x16x32_bf16 v[130:133], v[138:141], v[154:157], v[130:133]
	v_mfma_f32_16x16x32_bf16 v[126:129], v[146:149], v[154:157], v[126:129]
	v_mfma_f32_16x16x32_bf16 v[114:117], v[138:141], v[186:189], v[114:117]
	v_mfma_f32_16x16x32_bf16 v[110:113], v[146:149], v[186:189], v[110:113]
	v_mfma_f32_16x16x32_bf16 v[98:101], v[138:141], v[194:197], v[98:101]
	v_mfma_f32_16x16x32_bf16 v[94:97], v[146:149], v[194:197], v[94:97]
	v_mfma_f32_16x16x32_bf16 v[82:85], v[138:141], v[202:205], v[82:85]
	v_mfma_f32_16x16x32_bf16 v[78:81], v[146:149], v[202:205], v[78:81]
	s_barrier
	s_add_i32 s36, 0, 0x14000
	s_add_i32 s31, s31, s64
	v_add_u32_e32 v10, s36, v234
	v_lshl_add_u64 v[210:211], s[12:13], 0, v[164:165]
	s_mov_b32 m0, s31
	ds_read_b128 v[206:209], v10
	ds_read_b128 v[242:245], v10 offset:1024
	ds_read_b128 v[246:249], v10 offset:2048
	ds_read_b128 v[250:253], v10 offset:3072
	global_load_lds_dwordx4 v[210:211], off
	v_lshl_add_u64 v[216:217], s[12:13], 0, v[160:161]
	s_add_i32 m0, s31, 0x2000
	s_nop 0
	global_load_lds_dwordx4 v[216:217], off
	s_barrier
	s_waitcnt lgkmcnt(0)
	v_mfma_f32_16x16x32_bf16 v[122:125], v[206:209], v[150:153], 0
	v_mfma_f32_16x16x32_bf16 v[118:121], v[246:249], v[150:153], 0
	v_mfma_f32_16x16x32_bf16 v[106:109], v[206:209], v[182:185], 0
	v_mfma_f32_16x16x32_bf16 v[102:105], v[246:249], v[182:185], 0
	v_mfma_f32_16x16x32_bf16 v[90:93], v[206:209], v[190:193], 0
	v_mfma_f32_16x16x32_bf16 v[86:89], v[246:249], v[190:193], 0
	v_mfma_f32_16x16x32_bf16 v[74:77], v[206:209], v[198:201], 0
	v_mfma_f32_16x16x32_bf16 v[70:73], v[246:249], v[198:201], 0
	v_mfma_f32_16x16x32_bf16 v[122:125], v[242:245], v[154:157], v[122:125]
	v_mfma_f32_16x16x32_bf16 v[118:121], v[250:253], v[154:157], v[118:121]
	v_mfma_f32_16x16x32_bf16 v[106:109], v[242:245], v[186:189], v[106:109]
	v_mfma_f32_16x16x32_bf16 v[102:105], v[250:253], v[186:189], v[102:105]
	v_mfma_f32_16x16x32_bf16 v[90:93], v[242:245], v[194:197], v[90:93]
	v_mfma_f32_16x16x32_bf16 v[86:89], v[250:253], v[194:197], v[86:89]
	v_mfma_f32_16x16x32_bf16 v[74:77], v[242:245], v[202:205], v[74:77]
	v_mfma_f32_16x16x32_bf16 v[70:73], v[250:253], v[202:205], v[70:73]
	s_mov_b32 m0, s65
	v_lshl_add_u64 v[222:223], s[8:9], 0, v[162:163]
	s_barrier
	ds_read_b128 v[150:153], v240 offset:16384
	ds_read_b128 v[154:157], v240 offset:17408
	ds_read_b128 v[182:185], v240 offset:18432
	ds_read_b128 v[186:189], v240 offset:19456
	ds_read_b128 v[190:193], v240 offset:20480
	ds_read_b128 v[194:197], v240 offset:21504
	ds_read_b128 v[198:201], v240 offset:22528
	ds_read_b128 v[202:205], v240 offset:23552
	global_load_lds_dwordx4 v[222:223], off
	v_lshl_add_u64 v[224:225], s[8:9], 0, v[8:9]
	s_mov_b32 m0, s71
	s_nop 0
	global_load_lds_dwordx4 v[224:225], off
	s_barrier
	s_waitcnt lgkmcnt(0)
	v_mfma_f32_16x16x32_bf16 v[66:69], v[134:137], v[150:153], 0
	v_mfma_f32_16x16x32_bf16 v[62:65], v[142:145], v[150:153], 0
	v_mfma_f32_16x16x32_bf16 v[50:53], v[134:137], v[182:185], 0
	v_mfma_f32_16x16x32_bf16 v[46:49], v[142:145], v[182:185], 0
	v_mfma_f32_16x16x32_bf16 v[34:37], v[134:137], v[190:193], 0
	v_mfma_f32_16x16x32_bf16 v[30:33], v[142:145], v[190:193], 0
	v_mfma_f32_16x16x32_bf16 v[18:21], v[134:137], v[198:201], 0
	v_mfma_f32_16x16x32_bf16 v[12:15], v[142:145], v[198:201], 0
	v_mfma_f32_16x16x32_bf16 v[66:69], v[138:141], v[154:157], v[66:69]
	v_mfma_f32_16x16x32_bf16 v[62:65], v[146:149], v[154:157], v[62:65]
	v_mfma_f32_16x16x32_bf16 v[50:53], v[138:141], v[186:189], v[50:53]
	v_mfma_f32_16x16x32_bf16 v[46:49], v[146:149], v[186:189], v[46:49]
	v_mfma_f32_16x16x32_bf16 v[34:37], v[138:141], v[194:197], v[34:37]
	v_mfma_f32_16x16x32_bf16 v[30:33], v[146:149], v[194:197], v[30:33]
	v_mfma_f32_16x16x32_bf16 v[18:21], v[138:141], v[202:205], v[18:21]
	v_mfma_f32_16x16x32_bf16 v[12:15], v[146:149], v[202:205], v[12:15]
	s_barrier
; #define PG8_STAGE(bufoff, gbase, voff) do { _Pragma("unroll") for (int _i = 0; _i < 2; ++_i) \
;         __builtin_amdgcn_global_load_lds((const unsigned*)((const char*)(gbase) + (voff)[_i]), (LAS unsigned*)(lds + (bufoff) + ldsw + _i * 8192), 16, 0, 0); } while (0)
; #define PG8_LDA(dst, b, h) do { _Pragma("unroll") for (int m = 0; m < 4; ++m) _Pragma("unroll") for (int k = 0; k < 2; ++k) dst[m][k] = *(const LAS bf16x8*)(lds + PG8_SA(b, h) + aoff + m * 2048 + k * 1024); } while (0)
; #define PG8_LDB(dst, b, h) do { _Pragma("unroll") for (int n = 0; n < 2; ++n) _Pragma("unroll") for (int k = 0; k < 2; ++k) dst[n][k] = *(const LAS bf16x8*)(lds + PG8_SB(b, h) + boff + n * 2048 + k * 1024); } while (0)
; #define PG8_MMA(ai, bj, At, Bt) do { __builtin_amdgcn_s_setprio(1); _Pragma("unroll") for (int m = 0; m < 4; ++m) _Pragma("unroll") for (int n = 0; n < 2; ++n) _Pragma("unroll") for (int k = 0; k < 2; ++k) \
;         acc[ai][bj][m][n] = __builtin_amdgcn_mfma_f32_16x16x32_bf16(Bt[n][k], At[m][k], acc[ai][bj][m][n], 0, 0, 0); __builtin_amdgcn_s_setprio(0); } while (0)
; #define PG8_WAIT_V(n) asm volatile("s_waitcnt vmcnt(" #n ")" ::: "memory")
; #define PG8_WAIT_L(n) asm volatile("s_waitcnt lgkmcnt(" #n ")" ::: "memory")
; #define PG8_BAR __builtin_amdgcn_s_barrier()
; #define PG8_SCHED __builtin_amdgcn_sched_barrier(0)
; __device__ __forceinline__ void gemm_phase(const int bid, const int nblk, LAS unsigned char* lds, const int garg, const int chunk, const Params& p) {
;     ...
;             PG8_LDB(B0, 0, 0); PG8_SCHED; PG8_LDA(At, 0, 0); PG8_STAGE(PG8_SA(1, 1), a1 + hstepA, voffA);
;             PG8_WAIT_L(8); PG8_BAR; PG8_WAIT_L(0); PG8_MMA(0, 0, At, B0); PG8_BAR; PG8_SCHED;
;             PG8_LDB(B1, 0, 1); PG8_STAGE(PG8_SB(0, 0), b2, voffB);
;             PG8_BAR; PG8_WAIT_L(0); PG8_MMA(0, 1, At, B1); PG8_BAR;
;             PG8_LDA(At, 0, 1); PG8_STAGE(PG8_SA(0, 0), a2, voffA);
;             PG8_BAR; PG8_WAIT_L(0); PG8_MMA(1, 0, At, B0); PG8_BAR; PG8_SCHED;
;             PG8_STAGE(PG8_SB(0, 1), b2 + hstepB, voffB);
;             PG8_WAIT_V(6); PG8_BAR; PG8_MMA(1, 1, At, B1); PG8_BAR;
	s_add_u32 s12, s12, s66
	s_addc_u32 s13, s13, s67
	s_add_i32 s31, s36, s64
	v_lshl_add_u64 v[220:221], s[12:13], 0, v[164:165]
	s_mov_b32 m0, s31
	v_lshl_add_u64 v[226:227], s[12:13], 0, v[160:161]
	global_load_lds_dwordx4 v[220:221], off
	s_add_i32 m0, s31, 0x2000
	s_nop 0
	global_load_lds_dwordx4 v[226:227], off
	s_waitcnt vmcnt(6)
	s_barrier
	v_mfma_f32_16x16x32_bf16 v[58:61], v[206:209], v[150:153], 0
	v_mfma_f32_16x16x32_bf16 v[54:57], v[246:249], v[150:153], 0
	v_mfma_f32_16x16x32_bf16 v[42:45], v[206:209], v[182:185], 0
	v_mfma_f32_16x16x32_bf16 v[38:41], v[246:249], v[182:185], 0
	v_mfma_f32_16x16x32_bf16 v[26:29], v[206:209], v[190:193], 0
	v_mfma_f32_16x16x32_bf16 v[22:25], v[246:249], v[190:193], 0
	v_mfma_f32_16x16x32_bf16 v[4:7], v[206:209], v[198:201], 0
	v_mfma_f32_16x16x32_bf16 v[0:3], v[246:249], v[198:201], 0
	v_mfma_f32_16x16x32_bf16 v[58:61], v[242:245], v[154:157], v[58:61]
	v_mfma_f32_16x16x32_bf16 v[54:57], v[250:253], v[154:157], v[54:57]
	v_mfma_f32_16x16x32_bf16 v[42:45], v[242:245], v[186:189], v[42:45]
	v_mfma_f32_16x16x32_bf16 v[38:41], v[250:253], v[186:189], v[38:41]
	v_mfma_f32_16x16x32_bf16 v[26:29], v[242:245], v[194:197], v[26:29]
	v_mfma_f32_16x16x32_bf16 v[22:25], v[250:253], v[194:197], v[22:25]
	v_mfma_f32_16x16x32_bf16 v[4:7], v[242:245], v[202:205], v[4:7]
	v_mfma_f32_16x16x32_bf16 v[0:3], v[250:253], v[202:205], v[0:3]
	s_branch .Lk_mid
.LBB0_441:
	s_add_i32 s30, s8, 2
	s_add_u32 s12, s2, 0x80
	s_addc_u32 s9, s3, 0
	s_add_i32 s31, 0, 0x10000
	v_add_u32_e32 v10, s31, v234
	ds_read_b128 v[134:137], v10
	ds_read_b128 v[138:141], v10 offset:1024
	ds_read_b128 v[142:145], v10 offset:2048
	ds_read_b128 v[146:149], v10 offset:3072
	s_cmp_eq_u32 s27, s8
	s_cselect_b32 s8, s74, s12
	s_cselect_b32 s9, s75, s9
	s_cselect_b32 s13, s79, s15
	s_cselect_b32 s12, s78, s14
	v_lshl_add_u64 v[12:13], s[2:3], 0, v[176:177]
	s_add_i32 m0, s65, 0xc000
	ds_read_b128 v[150:153], v240
	ds_read_b128 v[154:157], v240 offset:1024
	ds_read_b128 v[182:185], v240 offset:2048
	ds_read_b128 v[186:189], v240 offset:3072
	ds_read_b128 v[190:193], v240 offset:4096
	ds_read_b128 v[194:197], v240 offset:5120
	ds_read_b128 v[198:201], v240 offset:6144
	ds_read_b128 v[202:205], v240 offset:7168
	global_load_lds_dwordx4 v[12:13], off
	v_lshl_add_u64 v[12:13], s[2:3], 0, v[178:179]
	s_add_i32 m0, s65, 0xe000
	s_nop 0
	global_load_lds_dwordx4 v[12:13], off
	s_waitcnt lgkmcnt(8)
	s_barrier
	s_waitcnt lgkmcnt(0)
	v_mfma_f32_16x16x32_bf16 v[130:133], v[134:137], v[150:153], v[130:133]
	v_mfma_f32_16x16x32_bf16 v[126:129], v[142:145], v[150:153], v[126:129]
	v_mfma_f32_16x16x32_bf16 v[114:117], v[134:137], v[182:185], v[114:117]
	v_mfma_f32_16x16x32_bf16 v[110:113], v[142:145], v[182:185], v[110:113]
	v_mfma_f32_16x16x32_bf16 v[98:101], v[134:137], v[190:193], v[98:101]
	v_mfma_f32_16x16x32_bf16 v[94:97], v[142:145], v[190:193], v[94:97]
	v_mfma_f32_16x16x32_bf16 v[82:85], v[134:137], v[198:201], v[82:85]
	v_mfma_f32_16x16x32_bf16 v[78:81], v[142:145], v[198:201], v[78:81]
	v_mfma_f32_16x16x32_bf16 v[130:133], v[138:141], v[154:157], v[130:133]
	v_mfma_f32_16x16x32_bf16 v[126:129], v[146:149], v[154:157], v[126:129]
	v_mfma_f32_16x16x32_bf16 v[114:117], v[138:141], v[186:189], v[114:117]
	v_mfma_f32_16x16x32_bf16 v[110:113], v[146:149], v[186:189], v[110:113]
	v_mfma_f32_16x16x32_bf16 v[98:101], v[138:141], v[194:197], v[98:101]
	v_mfma_f32_16x16x32_bf16 v[94:97], v[146:149], v[194:197], v[94:97]
	v_mfma_f32_16x16x32_bf16 v[82:85], v[138:141], v[202:205], v[82:85]
	v_mfma_f32_16x16x32_bf16 v[78:81], v[146:149], v[202:205], v[78:81]
	s_barrier
	s_add_i32 s36, 0, 0x14000
	s_add_i32 s31, s31, s64
	v_add_u32_e32 v10, s36, v234
	v_lshl_add_u64 v[210:211], s[12:13], 0, v[164:165]
	s_mov_b32 m0, s31
	ds_read_b128 v[206:209], v10
	ds_read_b128 v[242:245], v10 offset:1024
	ds_read_b128 v[246:249], v10 offset:2048
	ds_read_b128 v[250:253], v10 offset:3072
	global_load_lds_dwordx4 v[210:211], off
	v_lshl_add_u64 v[216:217], s[12:13], 0, v[160:161]
	s_add_i32 m0, s31, 0x2000
	s_nop 0
	global_load_lds_dwordx4 v[216:217], off
	s_barrier
	s_waitcnt lgkmcnt(0)
	v_mfma_f32_16x16x32_bf16 v[122:125], v[206:209], v[150:153], v[122:125]
	v_mfma_f32_16x16x32_bf16 v[118:121], v[246:249], v[150:153], v[118:121]
	v_mfma_f32_16x16x32_bf16 v[106:109], v[206:209], v[182:185], v[106:109]
	v_mfma_f32_16x16x32_bf16 v[102:105], v[246:249], v[182:185], v[102:105]
	v_mfma_f32_16x16x32_bf16 v[90:93], v[206:209], v[190:193], v[90:93]
	v_mfma_f32_16x16x32_bf16 v[86:89], v[246:249], v[190:193], v[86:89]
	v_mfma_f32_16x16x32_bf16 v[74:77], v[206:209], v[198:201], v[74:77]
	v_mfma_f32_16x16x32_bf16 v[70:73], v[246:249], v[198:201], v[70:73]
	v_mfma_f32_16x16x32_bf16 v[122:125], v[242:245], v[154:157], v[122:125]
	v_mfma_f32_16x16x32_bf16 v[118:121], v[250:253], v[154:157], v[118:121]
	v_mfma_f32_16x16x32_bf16 v[106:109], v[242:245], v[186:189], v[106:109]
	v_mfma_f32_16x16x32_bf16 v[102:105], v[250:253], v[186:189], v[102:105]
	v_mfma_f32_16x16x32_bf16 v[90:93], v[242:245], v[194:197], v[90:93]
	v_mfma_f32_16x16x32_bf16 v[86:89], v[250:253], v[194:197], v[86:89]
	v_mfma_f32_16x16x32_bf16 v[74:77], v[242:245], v[202:205], v[74:77]
	v_mfma_f32_16x16x32_bf16 v[70:73], v[250:253], v[202:205], v[70:73]
	s_mov_b32 m0, s65
	v_lshl_add_u64 v[222:223], s[8:9], 0, v[162:163]
	s_barrier
	ds_read_b128 v[150:153], v240 offset:16384
	ds_read_b128 v[154:157], v240 offset:17408
	ds_read_b128 v[182:185], v240 offset:18432
	ds_read_b128 v[186:189], v240 offset:19456
	ds_read_b128 v[190:193], v240 offset:20480
	ds_read_b128 v[194:197], v240 offset:21504
	ds_read_b128 v[198:201], v240 offset:22528
	ds_read_b128 v[202:205], v240 offset:23552
	global_load_lds_dwordx4 v[222:223], off
	v_lshl_add_u64 v[224:225], s[8:9], 0, v[8:9]
	s_mov_b32 m0, s71
	s_nop 0
	global_load_lds_dwordx4 v[224:225], off
	s_barrier
; #define PG8_STAGE(bufoff, gbase, voff) do { _Pragma("unroll") for (int _i = 0; _i < 2; ++_i) \
;         __builtin_amdgcn_global_load_lds((const unsigned*)((const char*)(gbase) + (voff)[_i]), (LAS unsigned*)(lds + (bufoff) + ldsw + _i * 8192), 16, 0, 0); } while (0)
; #define PG8_MMA(ai, bj, At, Bt) do { __builtin_amdgcn_s_setprio(1); _Pragma("unroll") for (int m = 0; m < 4; ++m) _Pragma("unroll") for (int n = 0; n < 2; ++n) _Pragma("unroll") for (int k = 0; k < 2; ++k) \
;         acc[ai][bj][m][n] = __builtin_amdgcn_mfma_f32_16x16x32_bf16(Bt[n][k], At[m][k], acc[ai][bj][m][n], 0, 0, 0); __builtin_amdgcn_s_setprio(0); } while (0)
; #define PG8_WAIT_V(n) asm volatile("s_waitcnt vmcnt(" #n ")" ::: "memory")
; #define PG8_WAIT_L(n) asm volatile("s_waitcnt lgkmcnt(" #n ")" ::: "memory")
; #define PG8_BAR __builtin_amdgcn_s_barrier()
; #define PG8_SCHED __builtin_amdgcn_sched_barrier(0)
; __device__ __forceinline__ void gemm_phase(const int bid, const int nblk, LAS unsigned char* lds, const int garg, const int chunk, const Params& p) {
;     ...
;             PG8_BAR; PG8_WAIT_L(0); PG8_MMA(1, 0, At, B0); PG8_BAR; PG8_SCHED;
;             PG8_STAGE(PG8_SB(0, 1), b2 + hstepB, voffB);
;             PG8_WAIT_V(6); PG8_BAR; PG8_MMA(1, 1, At, B1); PG8_BAR;
	s_waitcnt lgkmcnt(0)
	v_mfma_f32_16x16x32_bf16 v[66:69], v[134:137], v[150:153], v[66:69]
	v_mfma_f32_16x16x32_bf16 v[62:65], v[142:145], v[150:153], v[62:65]
	v_mfma_f32_16x16x32_bf16 v[50:53], v[134:137], v[182:185], v[50:53]
	v_mfma_f32_16x16x32_bf16 v[46:49], v[142:145], v[182:185], v[46:49]
	v_mfma_f32_16x16x32_bf16 v[34:37], v[134:137], v[190:193], v[34:37]
	v_mfma_f32_16x16x32_bf16 v[30:33], v[142:145], v[190:193], v[30:33]
	v_mfma_f32_16x16x32_bf16 v[18:21], v[134:137], v[198:201], v[18:21]
	v_mfma_f32_16x16x32_bf16 v[12:15], v[142:145], v[198:201], v[14:17]
	v_mfma_f32_16x16x32_bf16 v[66:69], v[138:141], v[154:157], v[66:69]
	v_mfma_f32_16x16x32_bf16 v[62:65], v[146:149], v[154:157], v[62:65]
	v_mfma_f32_16x16x32_bf16 v[50:53], v[138:141], v[186:189], v[50:53]
	v_mfma_f32_16x16x32_bf16 v[46:49], v[146:149], v[186:189], v[46:49]
	v_mfma_f32_16x16x32_bf16 v[34:37], v[138:141], v[194:197], v[34:37]
	v_mfma_f32_16x16x32_bf16 v[30:33], v[146:149], v[194:197], v[30:33]
	v_mfma_f32_16x16x32_bf16 v[18:21], v[138:141], v[202:205], v[18:21]
	v_mfma_f32_16x16x32_bf16 v[12:15], v[146:149], v[202:205], v[12:15]
	s_barrier
	s_add_u32 s12, s12, s66
	s_addc_u32 s13, s13, s67
	s_add_i32 s31, s36, s64
	v_lshl_add_u64 v[220:221], s[12:13], 0, v[164:165]
	s_mov_b32 m0, s31
	v_lshl_add_u64 v[226:227], s[12:13], 0, v[160:161]
	global_load_lds_dwordx4 v[220:221], off
	s_add_i32 m0, s31, 0x2000
	s_nop 0
	global_load_lds_dwordx4 v[226:227], off
	s_waitcnt vmcnt(6)
	s_barrier
	v_mfma_f32_16x16x32_bf16 v[58:61], v[206:209], v[150:153], v[58:61]
	v_mfma_f32_16x16x32_bf16 v[54:57], v[246:249], v[150:153], v[54:57]
	v_mfma_f32_16x16x32_bf16 v[42:45], v[206:209], v[182:185], v[42:45]
	v_mfma_f32_16x16x32_bf16 v[38:41], v[246:249], v[182:185], v[38:41]
	v_mfma_f32_16x16x32_bf16 v[26:29], v[206:209], v[190:193], v[26:29]
	v_mfma_f32_16x16x32_bf16 v[22:25], v[246:249], v[190:193], v[22:25]
	v_mfma_f32_16x16x32_bf16 v[4:7], v[206:209], v[198:201], v[4:7]
	v_mfma_f32_16x16x32_bf16 v[0:3], v[246:249], v[198:201], v[0:3]
	v_mfma_f32_16x16x32_bf16 v[58:61], v[242:245], v[154:157], v[58:61]
	v_mfma_f32_16x16x32_bf16 v[54:57], v[250:253], v[154:157], v[54:57]
	v_mfma_f32_16x16x32_bf16 v[42:45], v[242:245], v[186:189], v[42:45]
	v_mfma_f32_16x16x32_bf16 v[38:41], v[250:253], v[186:189], v[38:41]
	v_mfma_f32_16x16x32_bf16 v[26:29], v[242:245], v[194:197], v[26:29]
	v_mfma_f32_16x16x32_bf16 v[22:25], v[250:253], v[194:197], v[22:25]
	v_mfma_f32_16x16x32_bf16 v[4:7], v[242:245], v[202:205], v[4:7]
	v_mfma_f32_16x16x32_bf16 v[0:3], v[250:253], v[202:205], v[0:3]
; #define PG8_STAGE(bufoff, gbase, voff) do { _Pragma("unroll") for (int _i = 0; _i < 2; ++_i) \
;         __builtin_amdgcn_global_load_lds((const unsigned*)((const char*)(gbase) + (voff)[_i]), (LAS unsigned*)(lds + (bufoff) + ldsw + _i * 8192), 16, 0, 0); } while (0)
; #define PG8_LDA(dst, b, h) do { _Pragma("unroll") for (int m = 0; m < 4; ++m) _Pragma("unroll") for (int k = 0; k < 2; ++k) dst[m][k] = *(const LAS bf16x8*)(lds + PG8_SA(b, h) + aoff + m * 2048 + k * 1024); } while (0)
; #define PG8_LDB(dst, b, h) do { _Pragma("unroll") for (int n = 0; n < 2; ++n) _Pragma("unroll") for (int k = 0; k < 2; ++k) dst[n][k] = *(const LAS bf16x8*)(lds + PG8_SB(b, h) + boff + n * 2048 + k * 1024); } while (0)
; #define PG8_MMA(ai, bj, At, Bt) do { __builtin_amdgcn_s_setprio(1); _Pragma("unroll") for (int m = 0; m < 4; ++m) _Pragma("unroll") for (int n = 0; n < 2; ++n) _Pragma("unroll") for (int k = 0; k < 2; ++k) \
;         acc[ai][bj][m][n] = __builtin_amdgcn_mfma_f32_16x16x32_bf16(Bt[n][k], At[m][k], acc[ai][bj][m][n], 0, 0, 0); __builtin_amdgcn_s_setprio(0); } while (0)
; #define PG8_WAIT_V(n) asm volatile("s_waitcnt vmcnt(" #n ")" ::: "memory")
; #define PG8_WAIT_L(n) asm volatile("s_waitcnt lgkmcnt(" #n ")" ::: "memory")
; #define PG8_BAR __builtin_amdgcn_s_barrier()
; #define PG8_SCHED __builtin_amdgcn_sched_barrier(0)
; __device__ __forceinline__ void gemm_phase(const int bid, const int nblk, LAS unsigned char* lds, const int garg, const int chunk, const Params& p) {
;     ...
;             PG8_LDB(B0, 1, 0); PG8_SCHED; PG8_LDA(At, 1, 0); PG8_STAGE(PG8_SA(0, 1), a2 + hstepA, voffA);
;             PG8_WAIT_L(8); PG8_BAR; PG8_WAIT_L(0); PG8_MMA(0, 0, At, B0); PG8_BAR; PG8_SCHED;
;             PG8_LDB(B1, 1, 1); PG8_STAGE(PG8_SB(1, 0), b3, voffB);
;             PG8_BAR; PG8_WAIT_L(0); PG8_MMA(0, 1, At, B1); PG8_BAR;
;             PG8_LDA(At, 1, 1); PG8_STAGE(PG8_SA(1, 0), a3, voffA);
;             PG8_BAR; PG8_WAIT_L(0); PG8_MMA(1, 0, At, B0); PG8_BAR; PG8_SCHED;
;             PG8_STAGE(PG8_SB(1, 1), b3 + hstepB, voffB);
;             PG8_WAIT_V(6); PG8_BAR; PG8_MMA(1, 1, At, B1); PG8_BAR;
.Lk_mid:
	s_add_i32 s12, 0, 0x18000
	v_add_u32_e32 v10, s12, v234
	s_barrier
	ds_read_b128 v[134:137], v10
	ds_read_b128 v[138:141], v10 offset:1024
	ds_read_b128 v[142:145], v10 offset:2048
	ds_read_b128 v[146:149], v10 offset:3072
	s_add_u32 s8, s8, s88
	s_addc_u32 s9, s9, s89
	s_mov_b32 m0, s63
	v_lshl_add_u64 v[16:17], s[8:9], 0, v[162:163]
	ds_read_b128 v[150:153], v240 offset:32768
	ds_read_b128 v[154:157], v240 offset:33792
	ds_read_b128 v[182:185], v240 offset:34816
	ds_read_b128 v[186:189], v240 offset:35840
	ds_read_b128 v[190:193], v240 offset:36864
	ds_read_b128 v[194:197], v240 offset:37888
	ds_read_b128 v[198:201], v240 offset:38912
	ds_read_b128 v[202:205], v240 offset:39936
	global_load_lds_dwordx4 v[16:17], off
	v_lshl_add_u64 v[16:17], s[8:9], 0, v[8:9]
	s_mov_b32 m0, s19
	s_nop 0
	global_load_lds_dwordx4 v[16:17], off
	s_waitcnt lgkmcnt(8)
	s_barrier
	s_waitcnt lgkmcnt(0)
	v_mfma_f32_16x16x32_bf16 v[130:133], v[134:137], v[150:153], v[130:133]
	v_mfma_f32_16x16x32_bf16 v[126:129], v[142:145], v[150:153], v[126:129]
	v_mfma_f32_16x16x32_bf16 v[114:117], v[134:137], v[182:185], v[114:117]
	v_mfma_f32_16x16x32_bf16 v[110:113], v[142:145], v[182:185], v[110:113]
	v_mfma_f32_16x16x32_bf16 v[98:101], v[134:137], v[190:193], v[98:101]
	v_mfma_f32_16x16x32_bf16 v[94:97], v[142:145], v[190:193], v[94:97]
	v_mfma_f32_16x16x32_bf16 v[82:85], v[134:137], v[198:201], v[82:85]
	v_mfma_f32_16x16x32_bf16 v[78:81], v[142:145], v[198:201], v[78:81]
	v_mfma_f32_16x16x32_bf16 v[130:133], v[138:141], v[154:157], v[130:133]
	v_mfma_f32_16x16x32_bf16 v[126:129], v[146:149], v[154:157], v[126:129]
	v_mfma_f32_16x16x32_bf16 v[114:117], v[138:141], v[186:189], v[114:117]
	v_mfma_f32_16x16x32_bf16 v[110:113], v[146:149], v[186:189], v[110:113]
	v_mfma_f32_16x16x32_bf16 v[98:101], v[138:141], v[194:197], v[98:101]
	v_mfma_f32_16x16x32_bf16 v[94:97], v[146:149], v[194:197], v[94:97]
	v_mfma_f32_16x16x32_bf16 v[82:85], v[138:141], v[202:205], v[82:85]
	v_mfma_f32_16x16x32_bf16 v[78:81], v[146:149], v[202:205], v[78:81]
	s_barrier
	s_add_i32 s8, 0, 0x1c000
	s_add_i32 s9, s12, s64
	v_add_u32_e32 v10, s8, v234
	v_lshl_add_u64 v[16:17], v[210:211], 0, s[92:93]
	s_mov_b32 m0, s9
	ds_read_b128 v[206:209], v10
	ds_read_b128 v[242:245], v10 offset:1024
	ds_read_b128 v[246:249], v10 offset:2048
	ds_read_b128 v[250:253], v10 offset:3072
	global_load_lds_dwordx4 v[16:17], off
	v_lshl_add_u64 v[16:17], v[216:217], 0, s[92:93]
	s_add_i32 m0, s9, 0x2000
	s_nop 0
	global_load_lds_dwordx4 v[16:17], off
	s_barrier
	s_waitcnt lgkmcnt(0)
	v_mfma_f32_16x16x32_bf16 v[122:125], v[206:209], v[150:153], v[122:125]
	v_mfma_f32_16x16x32_bf16 v[118:121], v[246:249], v[150:153], v[118:121]
	v_mfma_f32_16x16x32_bf16 v[106:109], v[206:209], v[182:185], v[106:109]
	v_mfma_f32_16x16x32_bf16 v[102:105], v[246:249], v[182:185], v[102:105]
	v_mfma_f32_16x16x32_bf16 v[90:93], v[206:209], v[190:193], v[90:93]
	v_mfma_f32_16x16x32_bf16 v[86:89], v[246:249], v[190:193], v[86:89]
	v_mfma_f32_16x16x32_bf16 v[74:77], v[206:209], v[198:201], v[74:77]
	v_mfma_f32_16x16x32_bf16 v[70:73], v[246:249], v[198:201], v[70:73]
	v_mfma_f32_16x16x32_bf16 v[122:125], v[242:245], v[154:157], v[122:125]
	v_mfma_f32_16x16x32_bf16 v[118:121], v[250:253], v[154:157], v[118:121]
	v_mfma_f32_16x16x32_bf16 v[106:109], v[242:245], v[186:189], v[106:109]
	v_mfma_f32_16x16x32_bf16 v[102:105], v[250:253], v[186:189], v[102:105]
	v_mfma_f32_16x16x32_bf16 v[90:93], v[242:245], v[194:197], v[90:93]
	v_mfma_f32_16x16x32_bf16 v[86:89], v[250:253], v[194:197], v[86:89]
	v_mfma_f32_16x16x32_bf16 v[74:77], v[242:245], v[202:205], v[74:77]
	v_mfma_f32_16x16x32_bf16 v[70:73], v[250:253], v[202:205], v[70:73]
	s_mov_b32 m0, s70
	v_lshl_add_u64 v[16:17], v[222:223], 0, s[92:93]
	s_barrier
	ds_read_b128 v[150:153], v240 offset:49152
	ds_read_b128 v[154:157], v240 offset:50176
	ds_read_b128 v[182:185], v240 offset:51200
	ds_read_b128 v[186:189], v240 offset:52224
	ds_read_b128 v[190:193], v240 offset:53248
	ds_read_b128 v[194:197], v240 offset:54272
	ds_read_b128 v[198:201], v240 offset:55296
	ds_read_b128 v[202:205], v240 offset:56320
	global_load_lds_dwordx4 v[16:17], off
	v_lshl_add_u64 v[16:17], v[224:225], 0, s[92:93]
	s_mov_b32 m0, s54
	s_nop 0
	global_load_lds_dwordx4 v[16:17], off
	s_barrier
	s_waitcnt lgkmcnt(0)
	v_mfma_f32_16x16x32_bf16 v[66:69], v[134:137], v[150:153], v[66:69]
	v_mfma_f32_16x16x32_bf16 v[62:65], v[142:145], v[150:153], v[62:65]
	v_mfma_f32_16x16x32_bf16 v[50:53], v[134:137], v[182:185], v[50:53]
	v_mfma_f32_16x16x32_bf16 v[46:49], v[142:145], v[182:185], v[46:49]
	v_mfma_f32_16x16x32_bf16 v[34:37], v[134:137], v[190:193], v[34:37]
	v_mfma_f32_16x16x32_bf16 v[30:33], v[142:145], v[190:193], v[30:33]
	v_mfma_f32_16x16x32_bf16 v[16:19], v[134:137], v[198:201], v[18:21]
	v_mfma_f32_16x16x32_bf16 v[12:15], v[142:145], v[198:201], v[12:15]
	v_mfma_f32_16x16x32_bf16 v[66:69], v[138:141], v[154:157], v[66:69]
	v_mfma_f32_16x16x32_bf16 v[62:65], v[146:149], v[154:157], v[62:65]
	v_mfma_f32_16x16x32_bf16 v[50:53], v[138:141], v[186:189], v[50:53]
	v_mfma_f32_16x16x32_bf16 v[46:49], v[146:149], v[186:189], v[46:49]
	v_mfma_f32_16x16x32_bf16 v[34:37], v[138:141], v[194:197], v[34:37]
	v_mfma_f32_16x16x32_bf16 v[30:33], v[146:149], v[194:197], v[30:33]
	v_mfma_f32_16x16x32_bf16 v[18:21], v[138:141], v[202:205], v[16:19]
	v_mfma_f32_16x16x32_bf16 v[14:17], v[146:149], v[202:205], v[12:15]
	s_barrier
	s_add_i32 s8, s8, s64
	v_lshl_add_u64 v[12:13], v[220:221], 0, s[92:93]
	s_mov_b32 m0, s8
	s_nop 0
	global_load_lds_dwordx4 v[12:13], off
	v_lshl_add_u64 v[12:13], v[226:227], 0, s[92:93]
	s_add_i32 m0, s8, 0x2000
	s_nop 0
	global_load_lds_dwordx4 v[12:13], off
	s_waitcnt vmcnt(6)
	s_barrier
	v_mfma_f32_16x16x32_bf16 v[58:61], v[206:209], v[150:153], v[58:61]
	v_mfma_f32_16x16x32_bf16 v[54:57], v[246:249], v[150:153], v[54:57]
	v_mfma_f32_16x16x32_bf16 v[42:45], v[206:209], v[182:185], v[42:45]
	v_mfma_f32_16x16x32_bf16 v[38:41], v[246:249], v[182:185], v[38:41]
	v_mfma_f32_16x16x32_bf16 v[26:29], v[206:209], v[190:193], v[26:29]
	v_mfma_f32_16x16x32_bf16 v[22:25], v[246:249], v[190:193], v[22:25]
	v_mfma_f32_16x16x32_bf16 v[4:7], v[206:209], v[198:201], v[4:7]
	v_mfma_f32_16x16x32_bf16 v[0:3], v[246:249], v[198:201], v[0:3]
	v_mfma_f32_16x16x32_bf16 v[58:61], v[242:245], v[154:157], v[58:61]
	v_mfma_f32_16x16x32_bf16 v[54:57], v[250:253], v[154:157], v[54:57]
	v_mfma_f32_16x16x32_bf16 v[42:45], v[242:245], v[186:189], v[42:45]
	v_mfma_f32_16x16x32_bf16 v[38:41], v[250:253], v[186:189], v[38:41]
	v_mfma_f32_16x16x32_bf16 v[26:29], v[242:245], v[194:197], v[26:29]
	v_mfma_f32_16x16x32_bf16 v[22:25], v[250:253], v[194:197], v[22:25]
	v_mfma_f32_16x16x32_bf16 v[4:7], v[242:245], v[202:205], v[4:7]
	v_mfma_f32_16x16x32_bf16 v[0:3], v[250:253], v[202:205], v[0:3]
	s_add_u32 s2, s2, 0x100
	s_addc_u32 s3, s3, 0
	s_add_u32 s14, s14, 0x100
	s_addc_u32 s15, s15, 0
	s_cmp_ge_i32 s30, s55
	s_mov_b32 s8, s30
	s_barrier
	s_cbranch_scc0 .LBB0_441
	s_branch .LBB0_443

; __device__ __forceinline__ void epi_dft(const f32x4 (&acc)[2][2][4][2], const Unit& u, char* Cb, unsigned cZ1, int wr, int wc, int fr, int fq) {
;     asm volatile("" : "+v"(fq), "+v"(fr));
;     bf16_t* fb = (bf16_t*)(Cb + (size_t)u.z1 * cZ1) + u.pn * BM;
;     const int r0 = u.pm * BM + wr * 64 + fr;
; #pragma unroll
;     for (int ai = 0; ai < 2; ++ai)
; #pragma unroll
;         for (int m = 0; m < 4; ++m) {
;             const int s = r0 + ai * HALF + m * 16;
;             bf16_t* rowp = fb + (long)s * DM;
;             bf16_t* mir = fb + (long)(SEQ - s) * DM;
; #pragma unroll
;             for (int bj = 0; bj < 2; ++bj) {
;                 const int c0 = bj * HALF + wc * 32 + 8 * fq;
;                 const f32x4 v0 = acc[ai][bj][m][0], v1 = acc[ai][bj][m][1];
;                 u32x4 w; w.x = cvt_pk_bf16(v0[0], v0[1]); w.y = cvt_pk_bf16(v0[2], v0[3]); w.z = cvt_pk_bf16(v1[0], v1[1]); w.w = cvt_pk_bf16(v1[2], v1[3]);
;                 *(u32x4*)(rowp + c0) = w;
;                 if (s != 0) {
;                     bf16_t* mg = mir + (248 - c0);
;                     mg[1] = (bf16_t)(w.w >> 16);
;                     *(unsigned*)(mg + 2) = cvt_pk_bf16(v1[2], v1[1]);
;                     u32x2 t; t.x = cvt_pk_bf16(v1[0], v0[3]); t.y = cvt_pk_bf16(v0[2], v0[1]);
;                     *(u32x2*)(mg + 4) = t;
;                     mir[(256 - c0) & 255] = (bf16_t)(w.x & 0xffffu);
;                 }
; __device__ __forceinline__ void gemm_phase(const int bid, const int nblk, LAS unsigned char* lds, const int garg, const int chunk, const Params& p) {
;     ...
;         {
;             int zE; asm volatile("s_mov_b32 %0, 0" : "=s"(zE));
;             const GemmDesc& de = p.g[garg + zE];
;             char* Cb = de.C + (size_t)chunk * de.cCh;
;             if (epi == E_BF16) epi_bf16(acc, cur, Cb, de.cZ1, de.cZ2, de.ldc, de.gelu_pn, wr, wc, fr, fq);
;             else if (epi == E_RESID) epi_resid(acc, cur, Cb, de.ldc, de.bias, wr, wc, fr, fq);
;             else if (epi == E_F32) epi_f32(acc, cur, Cb, de.cZ1, de.cZ2, de.ldc, wr, wc, fr, fq);
;             else if (epi == E_DFT) epi_dft(acc, cur, Cb, de.cZ1, wr, wc, fr, fq);
;             else if (epi == E_FFN) { const int layer = de.gelu_pn; epi_ffn(acc, cur, Cb, p.in[23 + zE] + layer * 3 * DFF, p.in[24 + zE] + layer * DFF, p.edge + zE, (long)de.nM * 2 * DFF, (LAS float*)(lds + STAGE_BYTES), wr, wc, fr, fq); }
.LBB0_443:
	s_setprio 0
	s_mov_b32 s30, 0
	s_ashr_i32 s31, s30, 31
	s_mul_i32 s3, s30, 0x90
	s_mul_hi_i32 s2, s30, 0x90
	s_add_u32 s90, s58, s3
	s_addc_u32 s91, s59, s2
	s_load_dword s8, s[90:91], 0x208
	s_load_dwordx2 s[2:3], s[90:91], 0x1d0
	s_mov_b64 s[52:53], 0
	s_mov_b64 s[72:73], 0
	s_waitcnt lgkmcnt(0)
	s_mul_i32 s9, s29, s8
	s_mul_hi_u32 s12, s28, s8
	s_add_i32 s12, s12, s9
	s_mul_i32 s8, s28, s8
	s_add_u32 s46, s2, s8
	s_addc_u32 s47, s3, s12
	s_mov_b64 s[2:3], -1
	s_cmp_lt_i32 s45, 4
	s_cbranch_scc1 .LBB0_544
	s_cmp_gt_i32 s45, 4
	s_cbranch_scc0 .LBB0_525
	s_cmp_gt_i32 s45, 5
	s_cbranch_scc0 .LBB0_481
	s_cmp_eq_u32 s45, 6
	s_mov_b64 s[72:73], -1
	s_cbranch_scc0 .LBB0_480
	s_load_dword s2, s[90:91], 0x1f8
	s_ashr_i32 s3, s18, 31
	v_mov_b32_e32 v10, v233
	v_mov_b32_e32 v12, v159
	s_waitcnt lgkmcnt(0)
	s_mul_hi_u32 s8, s2, s18
	s_mul_i32 s3, s2, s3
	s_add_i32 s8, s8, s3
	s_mul_i32 s2, s2, s18
	s_add_u32 s9, s46, s2
	s_addc_u32 s8, s47, s8
	s_lshl_b32 s2, s61, 8
	s_ashr_i32 s3, s2, 31
	s_lshl_b64 s[2:3], s[2:3], 1
	s_add_u32 s2, s9, s2
	s_addc_u32 s3, s8, s3
	s_lshl_b32 s8, s68, 8
	v_readlane_b32 s9, v255, 16
	s_add_i32 s8, s8, s9
	v_add_u32_e32 v138, s8, v12
	v_ashrrev_i32_e32 v139, 31, v138
	v_lshlrev_b64 v[134:135], 11, v[138:139]
	v_readlane_b32 s8, v255, 17
	v_lshl_add_u64 v[140:141], s[2:3], 0, v[134:135]
	v_sub_u32_e32 v134, 0x800, v138
	v_lshl_add_u32 v12, v10, 3, s8
	v_ashrrev_i32_e32 v135, 31, v134
	v_lshlrev_b64 v[134:135], 11, v[134:135]
	v_ashrrev_i32_e32 v13, 31, v12
	v_lshl_add_u64 v[144:145], s[2:3], 0, v[134:135]
	v_cmp_ne_u32_e32 vcc, 0, v138
	v_lshl_add_u64 v[142:143], v[12:13], 1, v[140:141]
	v_lshlrev_b64 v[140:141], 1, v[12:13]
	v_sub_u32_e32 v148, 0, v12
	v_cvt_pk_bf16_f32 v134, v130, v131
	v_cvt_pk_bf16_f32 v135, v132, v133
	v_cvt_pk_bf16_f32 v136, v126, v127
	v_cvt_pk_bf16_f32 v137, v128, v129
	global_store_dwordx4 v[142:143], v[134:137], off
	s_and_saveexec_b64 s[8:9], vcc
	s_cbranch_execz .LBB0_449
	v_sub_co_u32_e64 v146, s[12:13], v144, v140
	s_nop 1
	v_subb_co_u32_e64 v147, s[12:13], v145, v141, s[12:13]
	global_store_short_d16_hi v[146:147], v137, off offset:498
	v_cvt_pk_bf16_f32 v10, v128, v127
	global_store_dword v[146:147], v10, off offset:500
	v_and_b32_e32 v10, 0xf8, v148
	v_cvt_pk_bf16_f32 v136, v126, v133
	v_cvt_pk_bf16_f32 v137, v132, v131
	v_lshlrev_b32_e32 v10, 1, v10
	global_store_dwordx2 v[146:147], v[136:137], off offset:504
	v_lshl_add_u64 v[136:137], v[144:145], 0, v[10:11]
	global_store_short v[136:137], v134, off
